# attention Q loads with nt (streaming) hint
# baseline (speedup 1.0000x reference)
; DI void attn_item(const bf16_t* __restrict__ Qw_, const bf16_t* __restrict__ Kh, const bf16_t* __restrict__ Vh, const bf16_t* Gw, bf16_t* Ow,
;                   int NT, int kt0, int qw, float sinkv, char* lds) {
;     ...
;     const bf16_t* Qw = Qw_ + (size_t)r32 * LDK + hi * 8;
; #pragma unroll
;     for (int d0 = 0; d0 < 8; ++d0) qr[d0] = *(const bf16x8*)(Qw + d0 * 16);
; DI void phase_att(const Params& p, unsigned char* shm) {
;     ...
;     for (int it = blockIdx.x; it < 1024; it += gridDim.x) {
;         const int hp = it & 1, g = (it >> 1) & 3, n = it >> 3;
;         const int head = g * 4 + hp * 2 + (wid >> 2), qw = 32 * (wid & 3);
;         const int kfirst = n == 0 ? 0 : (n - 1) * 128, NT = (n == 0 || n == 127) ? 4 : 6, kt0 = kfirst - n * 128;
;         __syncthreads();
;         const size_t go = (size_t)(n * 128 + qw) * 2048 + head * 128;
;         att::attn_item(Z + (size_t)(n * 128 + qw) * 3072 + head * 128, Z + (size_t)kfirst * 3072 + 2048 + g * 128, Z + (size_t)kfirst * 3072 + 2560 + g * 128,
.LBB0_238:
	s_lshl_b32 s5, s51, 1
	s_bfe_u32 s15, s51, 0x20001
	s_ashr_i32 s54, s51, 3
	s_and_b32 s5, s5, 2
	s_lshl_b32 s4, s15, 2
	s_add_i32 s17, s5, s31
	s_lshl_b32 s58, s54, 7
	s_add_i32 s17, s17, s4
	s_add_i32 s14, s58, 0xffffff80
	s_cmp_lt_u32 s51, 8
	s_cselect_b64 s[20:21], -1, 0
	s_and_b64 s[4:5], s[20:21], exec
	s_cselect_b32 s16, 0, s14
	s_or_b32 s14, s58, s34
	s_sub_i32 s55, s16, s58
	s_mul_i32 s5, s14, 0x1800
	s_mul_hi_i32 s4, s14, 0x1800
	s_add_u32 s5, s11, s5
	s_addc_u32 s4, s22, s4
	s_lshl_b32 s18, s17, 8
	s_add_u32 s52, s5, s18
	s_addc_u32 s53, s4, 0
	s_mul_i32 s5, s16, 0x1800
	s_mul_hi_i32 s4, s16, 0x1800
	s_add_u32 s5, s11, s5
	s_addc_u32 s4, s22, s4
	s_lshl_b32 s15, s15, 8
	s_add_u32 s15, s5, s15
	s_addc_u32 s19, s4, 0
	s_add_u32 s4, s15, 0x1000
	s_addc_u32 s5, s19, 0
	s_add_u32 s18, s15, 0x1400
	s_addc_u32 s19, s19, 0
	s_barrier
	global_load_dwordx4 v[2:5], v200, s[18:19]
	global_load_dwordx4 v[6:9], v201, s[18:19]
	global_load_dwordx4 v[10:13], v200, s[4:5]
	global_load_dwordx4 v[14:17], v201, s[4:5]
	v_lshl_add_u64 v[18:19], s[52:53], 0, v[178:179]
	v_lshl_add_u64 v[18:19], v[18:19], 0, v[184:185]
	global_load_dwordx4 v[126:129], v[18:19], off nt
	global_load_dwordx4 v[122:125], v[18:19], off offset:32 nt
	global_load_dwordx4 v[118:121], v[18:19], off offset:64 nt
	global_load_dwordx4 v[114:117], v[18:19], off offset:96 nt
	global_load_dwordx4 v[110:113], v[18:19], off offset:128 nt
	global_load_dwordx4 v[106:109], v[18:19], off offset:160 nt
	global_load_dwordx4 v[102:105], v[18:19], off offset:192 nt
	global_load_dwordx4 v[98:101], v[18:19], off offset:224 nt
	s_lshl_b32 s15, s17, 2
	v_mov_b32_e32 v0, s15
	global_load_dword v0, v0, s[8:9]
	s_waitcnt vmcnt(0)
	s_cmp_lt_i32 s55, s37
	s_cselect_b64 s[56:57], -1, 0
	s_sub_i32 s15, s55, s34
	s_add_i32 s15, s15, 63
	s_cmpk_gt_i32 s15, 0x80
	s_cselect_b64 s[60:61], -1, 0
	s_or_b64 s[56:57], s[56:57], s[60:61]
	v_readfirstlane_b32 s52, v202
	s_andn2_b64 vcc, exec, s[56:57]
	s_waitcnt vmcnt(12)
	ds_write_b128 v208, v[2:5]
	s_waitcnt vmcnt(11)
	ds_write_b128 v209, v[6:9]
	s_waitcnt vmcnt(10)
	ds_write_b128 v210, v[10:13] offset:32768
	s_waitcnt vmcnt(9)
	ds_write_b128 v211, v[14:17] offset:32768
	s_waitcnt lgkmcnt(0)
	s_barrier
	ds_read_b128 v[2:5], v212 offset:32768
	ds_read_b128 v[6:9], v212 offset:40960
	s_waitcnt vmcnt(8) lgkmcnt(1)
	v_mfma_f32_32x32x16_bf16 v[18:33], v[2:5], v[126:129], 0
	ds_read_b128 v[34:37], v213 offset:32768
	ds_read_b128 v[38:41], v213 offset:40960
	s_waitcnt lgkmcnt(2)
	v_mfma_f32_32x32x16_bf16 v[2:17], v[6:9], v[126:129], 0
	s_waitcnt vmcnt(7) lgkmcnt(1)
	v_mfma_f32_32x32x16_bf16 v[18:33], v[34:37], v[122:125], v[18:33]
	s_waitcnt lgkmcnt(0)
	v_mfma_f32_32x32x16_bf16 v[2:17], v[38:41], v[122:125], v[2:17]
	ds_read_b128 v[34:37], v214 offset:32768
	ds_read_b128 v[38:41], v214 offset:40960
	s_waitcnt vmcnt(6) lgkmcnt(1)
	v_mfma_f32_32x32x16_bf16 v[18:33], v[34:37], v[118:121], v[18:33]
	s_waitcnt lgkmcnt(0)
	v_mfma_f32_32x32x16_bf16 v[2:17], v[38:41], v[118:121], v[2:17]
	ds_read_b128 v[34:37], v215 offset:32768
	ds_read_b128 v[38:41], v215 offset:40960
	s_waitcnt vmcnt(5) lgkmcnt(1)
	v_mfma_f32_32x32x16_bf16 v[18:33], v[34:37], v[114:117], v[18:33]
	s_waitcnt lgkmcnt(0)
	v_mfma_f32_32x32x16_bf16 v[2:17], v[38:41], v[114:117], v[2:17]
	ds_read_b128 v[34:37], v216 offset:32768
	ds_read_b128 v[38:41], v216 offset:40960
	s_waitcnt vmcnt(4) lgkmcnt(1)
	v_mfma_f32_32x32x16_bf16 v[18:33], v[34:37], v[110:113], v[18:33]
	s_waitcnt lgkmcnt(0)
	v_mfma_f32_32x32x16_bf16 v[2:17], v[38:41], v[110:113], v[2:17]
	ds_read_b128 v[34:37], v217 offset:32768
	ds_read_b128 v[38:41], v217 offset:40960
	s_waitcnt vmcnt(3) lgkmcnt(1)
	v_mfma_f32_32x32x16_bf16 v[18:33], v[34:37], v[106:109], v[18:33]
	s_waitcnt lgkmcnt(0)
	v_mfma_f32_32x32x16_bf16 v[2:17], v[38:41], v[106:109], v[2:17]
	ds_read_b128 v[34:37], v218 offset:32768
	ds_read_b128 v[38:41], v218 offset:40960
	s_waitcnt vmcnt(2) lgkmcnt(1)
	v_mfma_f32_32x32x16_bf16 v[18:33], v[34:37], v[102:105], v[18:33]
	ds_read_b128 v[34:37], v219 offset:32768
	s_waitcnt lgkmcnt(1)
	v_mfma_f32_32x32x16_bf16 v[2:17], v[38:41], v[102:105], v[2:17]
	ds_read_b128 v[38:41], v219 offset:40960
	s_waitcnt vmcnt(1) lgkmcnt(1)
	v_mfma_f32_32x32x16_bf16 v[18:33], v[34:37], v[98:101], v[18:33]
	s_waitcnt lgkmcnt(0)
	v_mfma_f32_32x32x16_bf16 v[2:17], v[38:41], v[98:101], v[2:17]
	s_cbranch_vccnz .LBB0_240
; DI void maskT(f32x16& p0, f32x16& p1, int kt, int qw, int r32, int hi) {
;     if ((kt - qw - 31 < -128) || (kt + 63 - qw > 128)) {
;         const int db = kt - (qw + r32) + 4 * hi;
; #pragma unroll
;         for (int r = 0; r < 16; ++r) { const int d = db + (r & 3) + 8 * (r >> 2);
;             p0[r] = (d >= -128 && d <= 128) ? p0[r] : -1e30f; p1[r] = (d + 32 >= -128 && d + 32 <= 128) ? p1[r] : -1e30f; }
;     }
; }
	v_or_b32_e32 v34, s55, v193
	v_sub_u32_e32 v34, v34, v192
	v_add_u32_e32 v35, 0x80, v34
	v_cmp_gt_u32_e32 vcc, s41, v35
	v_add_u32_e32 v35, 0xa0, v34
	s_nop 3
	v_cndmask_b32_e32 v18, v220, v18, vcc
	v_cmp_gt_u32_e32 vcc, s41, v35
	v_add_u32_e32 v35, 0x81, v34
	s_nop 0
	v_cndmask_b32_e32 v2, v220, v2, vcc
	v_cmp_gt_u32_e32 vcc, s41, v35
	v_add_u32_e32 v35, 0xa1, v34
	s_nop 0
	v_cndmask_b32_e32 v19, v220, v19, vcc
	v_cmp_gt_u32_e32 vcc, s41, v35
	v_add_u32_e32 v35, 0x82, v34
	s_nop 0
	v_cndmask_b32_e32 v3, v220, v3, vcc
	v_cmp_gt_u32_e32 vcc, s41, v35
	v_add_u32_e32 v35, 0xa2, v34
	s_nop 0
	v_cndmask_b32_e32 v20, v220, v20, vcc
	v_cmp_gt_u32_e32 vcc, s41, v35
	v_add_u32_e32 v35, 0x83, v34
	s_nop 0
	v_cndmask_b32_e32 v4, v220, v4, vcc
	v_cmp_gt_u32_e32 vcc, s41, v35
	v_add_u32_e32 v35, 0xa3, v34
	s_nop 0
	v_cndmask_b32_e32 v21, v220, v21, vcc
	v_cmp_gt_u32_e32 vcc, s41, v35
	v_add_u32_e32 v35, 0x88, v34
	s_nop 0
	v_cndmask_b32_e32 v5, v220, v5, vcc
	v_cmp_gt_u32_e32 vcc, s41, v35
	v_add_u32_e32 v35, 0xa8, v34
	s_nop 0
	v_cndmask_b32_e32 v22, v220, v22, vcc
	v_cmp_gt_u32_e32 vcc, s41, v35
	v_add_u32_e32 v35, 0x89, v34
	s_nop 0
	v_cndmask_b32_e32 v6, v220, v6, vcc
	v_cmp_gt_u32_e32 vcc, s41, v35
	v_add_u32_e32 v35, 0xa9, v34
	s_nop 0
	v_cndmask_b32_e32 v23, v220, v23, vcc
	v_cmp_gt_u32_e32 vcc, s41, v35
	v_add_u32_e32 v35, 0x8a, v34
	s_nop 0
	v_cndmask_b32_e32 v7, v220, v7, vcc
	v_cmp_gt_u32_e32 vcc, s41, v35
	v_add_u32_e32 v35, 0xaa, v34
	s_nop 0
	v_cndmask_b32_e32 v24, v220, v24, vcc
	v_cmp_gt_u32_e32 vcc, s41, v35
	v_add_u32_e32 v35, 0x8b, v34
	s_nop 0
	v_cndmask_b32_e32 v8, v220, v8, vcc
	v_cmp_gt_u32_e32 vcc, s41, v35
	v_add_u32_e32 v35, 0xab, v34
	s_nop 0
	v_cndmask_b32_e32 v25, v220, v25, vcc
	v_cmp_gt_u32_e32 vcc, s41, v35
	v_add_u32_e32 v35, 0x90, v34
	s_nop 0
	v_cndmask_b32_e32 v9, v220, v9, vcc
	v_cmp_gt_u32_e32 vcc, s41, v35
	v_add_u32_e32 v35, 0xb0, v34
	s_nop 0
	v_cndmask_b32_e32 v26, v220, v26, vcc
	v_cmp_gt_u32_e32 vcc, s41, v35
	v_add_u32_e32 v35, 0x91, v34
	s_nop 0
	v_cndmask_b32_e32 v10, v220, v10, vcc
	v_cmp_gt_u32_e32 vcc, s41, v35
	v_add_u32_e32 v35, 0xb1, v34
	s_nop 0
	v_cndmask_b32_e32 v27, v220, v27, vcc
	v_cmp_gt_u32_e32 vcc, s41, v35
	v_add_u32_e32 v35, 0x92, v34
	s_nop 0
	v_cndmask_b32_e32 v11, v220, v11, vcc
	v_cmp_gt_u32_e32 vcc, s41, v35
	v_add_u32_e32 v35, 0xb2, v34
	s_nop 0
	v_cndmask_b32_e32 v28, v220, v28, vcc
	v_cmp_gt_u32_e32 vcc, s41, v35
	v_add_u32_e32 v35, 0x93, v34
	s_nop 0
	v_cndmask_b32_e32 v12, v220, v12, vcc
	v_cmp_gt_u32_e32 vcc, s41, v35
	v_add_u32_e32 v35, 0xb3, v34
	s_nop 0
	v_cndmask_b32_e32 v29, v220, v29, vcc
	v_cmp_gt_u32_e32 vcc, s41, v35
	v_add_u32_e32 v35, 0x98, v34
	s_nop 0
	v_cndmask_b32_e32 v13, v220, v13, vcc
	v_cmp_gt_u32_e32 vcc, s41, v35
	v_add_u32_e32 v35, 0xb8, v34
	s_nop 0
	v_cndmask_b32_e32 v30, v220, v30, vcc
	v_cmp_gt_u32_e32 vcc, s41, v35
	v_add_u32_e32 v35, 0x99, v34
	s_nop 0
	v_cndmask_b32_e32 v14, v220, v14, vcc
	v_cmp_gt_u32_e32 vcc, s41, v35
	v_add_u32_e32 v35, 0xb9, v34
	s_nop 0
	v_cndmask_b32_e32 v31, v220, v31, vcc
	v_cmp_gt_u32_e32 vcc, s41, v35
	v_add_u32_e32 v35, 0x9a, v34
	s_nop 0
	v_cndmask_b32_e32 v15, v220, v15, vcc
	v_cmp_gt_u32_e32 vcc, s41, v35
	v_add_u32_e32 v35, 0xba, v34
	s_nop 0
	v_cndmask_b32_e32 v32, v220, v32, vcc
	v_cmp_gt_u32_e32 vcc, s41, v35
	v_add_u32_e32 v35, 0x9b, v34
	v_add_u32_e32 v34, 0xbb, v34
	v_cndmask_b32_e32 v16, v220, v16, vcc
	v_cmp_gt_u32_e32 vcc, s41, v35
	s_nop 1
	v_cndmask_b32_e32 v33, v220, v33, vcc
	v_cmp_gt_u32_e32 vcc, s41, v34
	s_nop 1
	v_cndmask_b32_e32 v17, v220, v17, vcc
